# v94 with default cache policy on the final output stores (non-temporal hint only on the norm-phase row loads)
# speedup vs baseline: 1.0041x; 1.0041x over previous
.LBB0_5762:
	s_cmp_gt_i32 s44, 22
	s_waitcnt lgkmcnt(0)
	s_cselect_b64 s[2:3], -1, 0
	s_cmp_lt_i32 s45, 23
	s_cselect_b64 s[4:5], -1, 0
	s_or_b64 s[2:3], s[2:3], s[4:5]
	s_and_b64 vcc, exec, s[2:3]
	s_cbranch_vccnz .LBB0_5820
	s_lshl_b32 s96, s22, 3
	s_lshr_b32 s97, s70, 6
	s_add_u32 s96, s96, s97
	s_lshl_b32 s97, s96, 4
	s_cmpk_ge_u32 s97, 0x8000
	s_cbranch_scc1 .Lnp22_done
	s_load_dwordx2 s[88:89], s[0:1], 0xb8
	s_load_dwordx2 s[90:91], s[0:1], 0xb0
	v_mbcnt_hi_u32_b32 v0, -1, v210
	v_lshlrev_b32_e32 v1, 4, v0
	s_waitcnt lgkmcnt(0)
	global_load_dwordx4 v[112:115], v1, s[90:91] nt
	global_load_dwordx4 v[116:119], v1, s[90:91] offset:1024 nt
	global_load_dwordx4 v[120:123], v1, s[90:91] offset:2048 nt
	global_load_dwordx4 v[124:127], v1, s[90:91] offset:3072 nt
	s_waitcnt vmcnt(0) lgkmcnt(0)
	s_add_u32 s98, s97, 0
	s_lshl_b32 s98, s98, 12
	v_add_u32_e32 v3, s98, v1
	global_load_dwordx4 v[16:19], v3, s[88:89] nt
	global_load_dwordx4 v[20:23], v3, s[88:89] offset:1024 nt
	global_load_dwordx4 v[24:27], v3, s[88:89] offset:2048 nt
	global_load_dwordx4 v[28:31], v3, s[88:89] offset:3072 nt
	s_add_u32 s98, s97, 1
	s_lshl_b32 s98, s98, 12
	v_add_u32_e32 v3, s98, v1
	global_load_dwordx4 v[32:35], v3, s[88:89] nt
	global_load_dwordx4 v[36:39], v3, s[88:89] offset:1024 nt
	global_load_dwordx4 v[40:43], v3, s[88:89] offset:2048 nt
	global_load_dwordx4 v[44:47], v3, s[88:89] offset:3072 nt
	s_add_u32 s98, s97, 2
	s_lshl_b32 s98, s98, 12
	v_add_u32_e32 v3, s98, v1
	global_load_dwordx4 v[48:51], v3, s[88:89] nt
	global_load_dwordx4 v[52:55], v3, s[88:89] offset:1024 nt
	global_load_dwordx4 v[56:59], v3, s[88:89] offset:2048 nt
	global_load_dwordx4 v[60:63], v3, s[88:89] offset:3072 nt
	s_add_u32 s98, s97, 3
	s_lshl_b32 s98, s98, 12
	v_add_u32_e32 v3, s98, v1
	global_load_dwordx4 v[64:67], v3, s[88:89] nt
	global_load_dwordx4 v[68:71], v3, s[88:89] offset:1024 nt
	global_load_dwordx4 v[72:75], v3, s[88:89] offset:2048 nt
	global_load_dwordx4 v[76:79], v3, s[88:89] offset:3072 nt
	s_add_u32 s98, s97, 4
	s_lshl_b32 s98, s98, 12
	v_add_u32_e32 v3, s98, v1
	global_load_dwordx4 v[80:83], v3, s[88:89] nt
	global_load_dwordx4 v[84:87], v3, s[88:89] offset:1024 nt
	global_load_dwordx4 v[88:91], v3, s[88:89] offset:2048 nt
	global_load_dwordx4 v[92:95], v3, s[88:89] offset:3072 nt
	s_add_u32 s98, s97, 5
	s_lshl_b32 s98, s98, 12
	v_add_u32_e32 v3, s98, v1
	global_load_dwordx4 v[96:99], v3, s[88:89] nt
	global_load_dwordx4 v[100:103], v3, s[88:89] offset:1024 nt
	global_load_dwordx4 v[104:107], v3, s[88:89] offset:2048 nt
	global_load_dwordx4 v[108:111], v3, s[88:89] offset:3072 nt
	s_waitcnt vmcnt(20)
	v_mul_f32_e32 v4, v16, v16
	v_fma_f32 v4, v17, v17, v4
	v_fma_f32 v4, v18, v18, v4
	v_fma_f32 v4, v19, v19, v4
	v_fma_f32 v4, v20, v20, v4
	v_fma_f32 v4, v21, v21, v4
	v_fma_f32 v4, v22, v22, v4
	v_fma_f32 v4, v23, v23, v4
	v_fma_f32 v4, v24, v24, v4
	v_fma_f32 v4, v25, v25, v4
	v_fma_f32 v4, v26, v26, v4
	v_fma_f32 v4, v27, v27, v4
	v_fma_f32 v4, v28, v28, v4
	v_fma_f32 v4, v29, v29, v4
	v_fma_f32 v4, v30, v30, v4
	v_fma_f32 v4, v31, v31, v4
	s_nop 1
	v_add_f32_dpp v5, v4, v4 quad_perm:[1,0,3,2] row_mask:0xf bank_mask:0xf
	s_nop 1
	v_add_f32_dpp v4, v5, v5 quad_perm:[2,3,0,1] row_mask:0xf bank_mask:0xf
	s_nop 1
	v_add_f32_dpp v5, v4, v4 row_half_mirror row_mask:0xf bank_mask:0xf
	s_nop 1
	v_add_f32_dpp v4, v5, v5 row_mirror row_mask:0xf bank_mask:0xf
	s_nop 1
	v_readlane_b32 s98, v4, 0
	v_readlane_b32 s99, v4, 16
	s_nop 3
	v_mov_b32_e32 v5, s98
	v_add_f32_e32 v5, s99, v5
	v_readlane_b32 s98, v4, 32
	v_readlane_b32 s99, v4, 48
	s_nop 3
	v_add_f32_e32 v5, s98, v5
	v_add_f32_e32 v5, s99, v5
	v_mul_f32_e32 v5, 0x3a800000, v5
	v_add_f32_e32 v5, 0x358637bd, v5
	v_rsq_f32_e32 v6, v5
	s_nop 0
	s_add_u32 s98, s97, 0
	v_pk_mul_f32 v[16:17], v[16:17], v[6:7] op_sel_hi:[1,0]
	v_pk_mul_f32 v[18:19], v[18:19], v[6:7] op_sel_hi:[1,0]
	v_pk_mul_f32 v[20:21], v[20:21], v[6:7] op_sel_hi:[1,0]
	v_pk_mul_f32 v[22:23], v[22:23], v[6:7] op_sel_hi:[1,0]
	v_pk_mul_f32 v[24:25], v[24:25], v[6:7] op_sel_hi:[1,0]
	v_pk_mul_f32 v[26:27], v[26:27], v[6:7] op_sel_hi:[1,0]
	v_pk_mul_f32 v[28:29], v[28:29], v[6:7] op_sel_hi:[1,0]
	v_pk_mul_f32 v[30:31], v[30:31], v[6:7] op_sel_hi:[1,0]
	v_pk_mul_f32 v[16:17], v[16:17], v[112:113]
	v_pk_mul_f32 v[18:19], v[18:19], v[114:115]
	v_pk_mul_f32 v[20:21], v[20:21], v[116:117]
	v_pk_mul_f32 v[22:23], v[22:23], v[118:119]
	v_pk_mul_f32 v[24:25], v[24:25], v[120:121]
	v_pk_mul_f32 v[26:27], v[26:27], v[122:123]
	v_pk_mul_f32 v[28:29], v[28:29], v[124:125]
	v_pk_mul_f32 v[30:31], v[30:31], v[126:127]
	s_lshl_b32 s99, s98, 12
	v_add_u32_e32 v8, s99, v1
	global_store_dwordx4 v8, v[16:19], s[88:89]
	global_store_dwordx4 v8, v[20:23], s[88:89] offset:1024
	global_store_dwordx4 v8, v[24:27], s[88:89] offset:2048
	global_store_dwordx4 v8, v[28:31], s[88:89] offset:3072
	s_add_u32 s98, s97, 6
	s_lshl_b32 s98, s98, 12
	v_add_u32_e32 v3, s98, v1
	global_load_dwordx4 v[16:19], v3, s[88:89] nt
	global_load_dwordx4 v[20:23], v3, s[88:89] offset:1024 nt
	global_load_dwordx4 v[24:27], v3, s[88:89] offset:2048 nt
	global_load_dwordx4 v[28:31], v3, s[88:89] offset:3072 nt
	s_waitcnt vmcnt(24)
	v_mul_f32_e32 v4, v32, v32
	v_fma_f32 v4, v33, v33, v4
	v_fma_f32 v4, v34, v34, v4
	v_fma_f32 v4, v35, v35, v4
	v_fma_f32 v4, v36, v36, v4
	v_fma_f32 v4, v37, v37, v4
	v_fma_f32 v4, v38, v38, v4
	v_fma_f32 v4, v39, v39, v4
	v_fma_f32 v4, v40, v40, v4
	v_fma_f32 v4, v41, v41, v4
	v_fma_f32 v4, v42, v42, v4
	v_fma_f32 v4, v43, v43, v4
	v_fma_f32 v4, v44, v44, v4
	v_fma_f32 v4, v45, v45, v4
	v_fma_f32 v4, v46, v46, v4
	v_fma_f32 v4, v47, v47, v4
	s_nop 1
	v_add_f32_dpp v5, v4, v4 quad_perm:[1,0,3,2] row_mask:0xf bank_mask:0xf
	s_nop 1
	v_add_f32_dpp v4, v5, v5 quad_perm:[2,3,0,1] row_mask:0xf bank_mask:0xf
	s_nop 1
	v_add_f32_dpp v5, v4, v4 row_half_mirror row_mask:0xf bank_mask:0xf
	s_nop 1
	v_add_f32_dpp v4, v5, v5 row_mirror row_mask:0xf bank_mask:0xf
	s_nop 1
	v_readlane_b32 s98, v4, 0
	v_readlane_b32 s99, v4, 16
	s_nop 3
	v_mov_b32_e32 v5, s98
	v_add_f32_e32 v5, s99, v5
	v_readlane_b32 s98, v4, 32
	v_readlane_b32 s99, v4, 48
	s_nop 3
	v_add_f32_e32 v5, s98, v5
	v_add_f32_e32 v5, s99, v5
	v_mul_f32_e32 v5, 0x3a800000, v5
	v_add_f32_e32 v5, 0x358637bd, v5
	v_rsq_f32_e32 v6, v5
	s_nop 0
	s_add_u32 s98, s97, 1
	v_pk_mul_f32 v[32:33], v[32:33], v[6:7] op_sel_hi:[1,0]
	v_pk_mul_f32 v[34:35], v[34:35], v[6:7] op_sel_hi:[1,0]
	v_pk_mul_f32 v[36:37], v[36:37], v[6:7] op_sel_hi:[1,0]
	v_pk_mul_f32 v[38:39], v[38:39], v[6:7] op_sel_hi:[1,0]
	v_pk_mul_f32 v[40:41], v[40:41], v[6:7] op_sel_hi:[1,0]
	v_pk_mul_f32 v[42:43], v[42:43], v[6:7] op_sel_hi:[1,0]
	v_pk_mul_f32 v[44:45], v[44:45], v[6:7] op_sel_hi:[1,0]
	v_pk_mul_f32 v[46:47], v[46:47], v[6:7] op_sel_hi:[1,0]
	v_pk_mul_f32 v[32:33], v[32:33], v[112:113]
	v_pk_mul_f32 v[34:35], v[34:35], v[114:115]
	v_pk_mul_f32 v[36:37], v[36:37], v[116:117]
	v_pk_mul_f32 v[38:39], v[38:39], v[118:119]
	v_pk_mul_f32 v[40:41], v[40:41], v[120:121]
	v_pk_mul_f32 v[42:43], v[42:43], v[122:123]
	v_pk_mul_f32 v[44:45], v[44:45], v[124:125]
	v_pk_mul_f32 v[46:47], v[46:47], v[126:127]
	s_lshl_b32 s99, s98, 12
	v_add_u32_e32 v8, s99, v1
	global_store_dwordx4 v8, v[32:35], s[88:89]
	global_store_dwordx4 v8, v[36:39], s[88:89] offset:1024
	global_store_dwordx4 v8, v[40:43], s[88:89] offset:2048
	global_store_dwordx4 v8, v[44:47], s[88:89] offset:3072
	s_add_u32 s98, s97, 7
	s_lshl_b32 s98, s98, 12
	v_add_u32_e32 v3, s98, v1
	global_load_dwordx4 v[32:35], v3, s[88:89] nt
	global_load_dwordx4 v[36:39], v3, s[88:89] offset:1024 nt
	global_load_dwordx4 v[40:43], v3, s[88:89] offset:2048 nt
	global_load_dwordx4 v[44:47], v3, s[88:89] offset:3072 nt
	s_waitcnt vmcnt(28)
	v_mul_f32_e32 v4, v48, v48
	v_fma_f32 v4, v49, v49, v4
	v_fma_f32 v4, v50, v50, v4
	v_fma_f32 v4, v51, v51, v4
	v_fma_f32 v4, v52, v52, v4
	v_fma_f32 v4, v53, v53, v4
	v_fma_f32 v4, v54, v54, v4
	v_fma_f32 v4, v55, v55, v4
	v_fma_f32 v4, v56, v56, v4
	v_fma_f32 v4, v57, v57, v4
	v_fma_f32 v4, v58, v58, v4
	v_fma_f32 v4, v59, v59, v4
	v_fma_f32 v4, v60, v60, v4
	v_fma_f32 v4, v61, v61, v4
	v_fma_f32 v4, v62, v62, v4
	v_fma_f32 v4, v63, v63, v4
	s_nop 1
	v_add_f32_dpp v5, v4, v4 quad_perm:[1,0,3,2] row_mask:0xf bank_mask:0xf
	s_nop 1
	v_add_f32_dpp v4, v5, v5 quad_perm:[2,3,0,1] row_mask:0xf bank_mask:0xf
	s_nop 1
	v_add_f32_dpp v5, v4, v4 row_half_mirror row_mask:0xf bank_mask:0xf
	s_nop 1
	v_add_f32_dpp v4, v5, v5 row_mirror row_mask:0xf bank_mask:0xf
	s_nop 1
	v_readlane_b32 s98, v4, 0
	v_readlane_b32 s99, v4, 16
	s_nop 3
	v_mov_b32_e32 v5, s98
	v_add_f32_e32 v5, s99, v5
	v_readlane_b32 s98, v4, 32
	v_readlane_b32 s99, v4, 48
	s_nop 3
	v_add_f32_e32 v5, s98, v5
	v_add_f32_e32 v5, s99, v5
	v_mul_f32_e32 v5, 0x3a800000, v5
	v_add_f32_e32 v5, 0x358637bd, v5
	v_rsq_f32_e32 v6, v5
	s_nop 0
	s_add_u32 s98, s97, 2
	v_pk_mul_f32 v[48:49], v[48:49], v[6:7] op_sel_hi:[1,0]
	v_pk_mul_f32 v[50:51], v[50:51], v[6:7] op_sel_hi:[1,0]
	v_pk_mul_f32 v[52:53], v[52:53], v[6:7] op_sel_hi:[1,0]
	v_pk_mul_f32 v[54:55], v[54:55], v[6:7] op_sel_hi:[1,0]
	v_pk_mul_f32 v[56:57], v[56:57], v[6:7] op_sel_hi:[1,0]
	v_pk_mul_f32 v[58:59], v[58:59], v[6:7] op_sel_hi:[1,0]
	v_pk_mul_f32 v[60:61], v[60:61], v[6:7] op_sel_hi:[1,0]
	v_pk_mul_f32 v[62:63], v[62:63], v[6:7] op_sel_hi:[1,0]
	v_pk_mul_f32 v[48:49], v[48:49], v[112:113]
	v_pk_mul_f32 v[50:51], v[50:51], v[114:115]
	v_pk_mul_f32 v[52:53], v[52:53], v[116:117]
	v_pk_mul_f32 v[54:55], v[54:55], v[118:119]
	v_pk_mul_f32 v[56:57], v[56:57], v[120:121]
	v_pk_mul_f32 v[58:59], v[58:59], v[122:123]
	v_pk_mul_f32 v[60:61], v[60:61], v[124:125]
	v_pk_mul_f32 v[62:63], v[62:63], v[126:127]
	s_lshl_b32 s99, s98, 12
	v_add_u32_e32 v8, s99, v1
	global_store_dwordx4 v8, v[48:51], s[88:89]
	global_store_dwordx4 v8, v[52:55], s[88:89] offset:1024
	global_store_dwordx4 v8, v[56:59], s[88:89] offset:2048
	global_store_dwordx4 v8, v[60:63], s[88:89] offset:3072
	s_add_u32 s98, s97, 8
	s_lshl_b32 s98, s98, 12
	v_add_u32_e32 v3, s98, v1
	global_load_dwordx4 v[48:51], v3, s[88:89] nt
	global_load_dwordx4 v[52:55], v3, s[88:89] offset:1024 nt
	global_load_dwordx4 v[56:59], v3, s[88:89] offset:2048 nt
	global_load_dwordx4 v[60:63], v3, s[88:89] offset:3072 nt
	s_waitcnt vmcnt(32)
	v_mul_f32_e32 v4, v64, v64
	v_fma_f32 v4, v65, v65, v4
	v_fma_f32 v4, v66, v66, v4
	v_fma_f32 v4, v67, v67, v4
	v_fma_f32 v4, v68, v68, v4
	v_fma_f32 v4, v69, v69, v4
	v_fma_f32 v4, v70, v70, v4
	v_fma_f32 v4, v71, v71, v4
	v_fma_f32 v4, v72, v72, v4
	v_fma_f32 v4, v73, v73, v4
	v_fma_f32 v4, v74, v74, v4
	v_fma_f32 v4, v75, v75, v4
	v_fma_f32 v4, v76, v76, v4
	v_fma_f32 v4, v77, v77, v4
	v_fma_f32 v4, v78, v78, v4
	v_fma_f32 v4, v79, v79, v4
	s_nop 1
	v_add_f32_dpp v5, v4, v4 quad_perm:[1,0,3,2] row_mask:0xf bank_mask:0xf
	s_nop 1
	v_add_f32_dpp v4, v5, v5 quad_perm:[2,3,0,1] row_mask:0xf bank_mask:0xf
	s_nop 1
	v_add_f32_dpp v5, v4, v4 row_half_mirror row_mask:0xf bank_mask:0xf
	s_nop 1
	v_add_f32_dpp v4, v5, v5 row_mirror row_mask:0xf bank_mask:0xf
	s_nop 1
	v_readlane_b32 s98, v4, 0
	v_readlane_b32 s99, v4, 16
	s_nop 3
	v_mov_b32_e32 v5, s98
	v_add_f32_e32 v5, s99, v5
	v_readlane_b32 s98, v4, 32
	v_readlane_b32 s99, v4, 48
	s_nop 3
	v_add_f32_e32 v5, s98, v5
	v_add_f32_e32 v5, s99, v5
	v_mul_f32_e32 v5, 0x3a800000, v5
	v_add_f32_e32 v5, 0x358637bd, v5
	v_rsq_f32_e32 v6, v5
	s_nop 0
	s_add_u32 s98, s97, 3
	v_pk_mul_f32 v[64:65], v[64:65], v[6:7] op_sel_hi:[1,0]
	v_pk_mul_f32 v[66:67], v[66:67], v[6:7] op_sel_hi:[1,0]
	v_pk_mul_f32 v[68:69], v[68:69], v[6:7] op_sel_hi:[1,0]
	v_pk_mul_f32 v[70:71], v[70:71], v[6:7] op_sel_hi:[1,0]
	v_pk_mul_f32 v[72:73], v[72:73], v[6:7] op_sel_hi:[1,0]
	v_pk_mul_f32 v[74:75], v[74:75], v[6:7] op_sel_hi:[1,0]
	v_pk_mul_f32 v[76:77], v[76:77], v[6:7] op_sel_hi:[1,0]
	v_pk_mul_f32 v[78:79], v[78:79], v[6:7] op_sel_hi:[1,0]
	v_pk_mul_f32 v[64:65], v[64:65], v[112:113]
	v_pk_mul_f32 v[66:67], v[66:67], v[114:115]
	v_pk_mul_f32 v[68:69], v[68:69], v[116:117]
	v_pk_mul_f32 v[70:71], v[70:71], v[118:119]
	v_pk_mul_f32 v[72:73], v[72:73], v[120:121]
	v_pk_mul_f32 v[74:75], v[74:75], v[122:123]
	v_pk_mul_f32 v[76:77], v[76:77], v[124:125]
	v_pk_mul_f32 v[78:79], v[78:79], v[126:127]
	s_lshl_b32 s99, s98, 12
	v_add_u32_e32 v8, s99, v1
	global_store_dwordx4 v8, v[64:67], s[88:89]
	global_store_dwordx4 v8, v[68:71], s[88:89] offset:1024
	global_store_dwordx4 v8, v[72:75], s[88:89] offset:2048
	global_store_dwordx4 v8, v[76:79], s[88:89] offset:3072
	s_add_u32 s98, s97, 9
	s_lshl_b32 s98, s98, 12
	v_add_u32_e32 v3, s98, v1
	global_load_dwordx4 v[64:67], v3, s[88:89] nt
	global_load_dwordx4 v[68:71], v3, s[88:89] offset:1024 nt
	global_load_dwordx4 v[72:75], v3, s[88:89] offset:2048 nt
	global_load_dwordx4 v[76:79], v3, s[88:89] offset:3072 nt
	s_waitcnt vmcnt(36)
	v_mul_f32_e32 v4, v80, v80
	v_fma_f32 v4, v81, v81, v4
	v_fma_f32 v4, v82, v82, v4
	v_fma_f32 v4, v83, v83, v4
	v_fma_f32 v4, v84, v84, v4
	v_fma_f32 v4, v85, v85, v4
	v_fma_f32 v4, v86, v86, v4
	v_fma_f32 v4, v87, v87, v4
	v_fma_f32 v4, v88, v88, v4
	v_fma_f32 v4, v89, v89, v4
	v_fma_f32 v4, v90, v90, v4
	v_fma_f32 v4, v91, v91, v4
	v_fma_f32 v4, v92, v92, v4
	v_fma_f32 v4, v93, v93, v4
	v_fma_f32 v4, v94, v94, v4
	v_fma_f32 v4, v95, v95, v4
	s_nop 1
	v_add_f32_dpp v5, v4, v4 quad_perm:[1,0,3,2] row_mask:0xf bank_mask:0xf
	s_nop 1
	v_add_f32_dpp v4, v5, v5 quad_perm:[2,3,0,1] row_mask:0xf bank_mask:0xf
	s_nop 1
	v_add_f32_dpp v5, v4, v4 row_half_mirror row_mask:0xf bank_mask:0xf
	s_nop 1
	v_add_f32_dpp v4, v5, v5 row_mirror row_mask:0xf bank_mask:0xf
	s_nop 1
	v_readlane_b32 s98, v4, 0
	v_readlane_b32 s99, v4, 16
	s_nop 3
	v_mov_b32_e32 v5, s98
	v_add_f32_e32 v5, s99, v5
	v_readlane_b32 s98, v4, 32
	v_readlane_b32 s99, v4, 48
	s_nop 3
	v_add_f32_e32 v5, s98, v5
	v_add_f32_e32 v5, s99, v5
	v_mul_f32_e32 v5, 0x3a800000, v5
	v_add_f32_e32 v5, 0x358637bd, v5
	v_rsq_f32_e32 v6, v5
	s_nop 0
	s_add_u32 s98, s97, 4
	v_pk_mul_f32 v[80:81], v[80:81], v[6:7] op_sel_hi:[1,0]
	v_pk_mul_f32 v[82:83], v[82:83], v[6:7] op_sel_hi:[1,0]
	v_pk_mul_f32 v[84:85], v[84:85], v[6:7] op_sel_hi:[1,0]
	v_pk_mul_f32 v[86:87], v[86:87], v[6:7] op_sel_hi:[1,0]
	v_pk_mul_f32 v[88:89], v[88:89], v[6:7] op_sel_hi:[1,0]
	v_pk_mul_f32 v[90:91], v[90:91], v[6:7] op_sel_hi:[1,0]
	v_pk_mul_f32 v[92:93], v[92:93], v[6:7] op_sel_hi:[1,0]
	v_pk_mul_f32 v[94:95], v[94:95], v[6:7] op_sel_hi:[1,0]
	v_pk_mul_f32 v[80:81], v[80:81], v[112:113]
	v_pk_mul_f32 v[82:83], v[82:83], v[114:115]
	v_pk_mul_f32 v[84:85], v[84:85], v[116:117]
	v_pk_mul_f32 v[86:87], v[86:87], v[118:119]
	v_pk_mul_f32 v[88:89], v[88:89], v[120:121]
	v_pk_mul_f32 v[90:91], v[90:91], v[122:123]
	v_pk_mul_f32 v[92:93], v[92:93], v[124:125]
	v_pk_mul_f32 v[94:95], v[94:95], v[126:127]
	s_lshl_b32 s99, s98, 12
	v_add_u32_e32 v8, s99, v1
	global_store_dwordx4 v8, v[80:83], s[88:89]
	global_store_dwordx4 v8, v[84:87], s[88:89] offset:1024
	global_store_dwordx4 v8, v[88:91], s[88:89] offset:2048
	global_store_dwordx4 v8, v[92:95], s[88:89] offset:3072
	s_add_u32 s98, s97, 10
	s_lshl_b32 s98, s98, 12
	v_add_u32_e32 v3, s98, v1
	global_load_dwordx4 v[80:83], v3, s[88:89] nt
	global_load_dwordx4 v[84:87], v3, s[88:89] offset:1024 nt
	global_load_dwordx4 v[88:91], v3, s[88:89] offset:2048 nt
	global_load_dwordx4 v[92:95], v3, s[88:89] offset:3072 nt
	s_waitcnt vmcnt(40)
	v_mul_f32_e32 v4, v96, v96
	v_fma_f32 v4, v97, v97, v4
	v_fma_f32 v4, v98, v98, v4
	v_fma_f32 v4, v99, v99, v4
	v_fma_f32 v4, v100, v100, v4
	v_fma_f32 v4, v101, v101, v4
	v_fma_f32 v4, v102, v102, v4
	v_fma_f32 v4, v103, v103, v4
	v_fma_f32 v4, v104, v104, v4
	v_fma_f32 v4, v105, v105, v4
	v_fma_f32 v4, v106, v106, v4
	v_fma_f32 v4, v107, v107, v4
	v_fma_f32 v4, v108, v108, v4
	v_fma_f32 v4, v109, v109, v4
	v_fma_f32 v4, v110, v110, v4
	v_fma_f32 v4, v111, v111, v4
	s_nop 1
	v_add_f32_dpp v5, v4, v4 quad_perm:[1,0,3,2] row_mask:0xf bank_mask:0xf
	s_nop 1
	v_add_f32_dpp v4, v5, v5 quad_perm:[2,3,0,1] row_mask:0xf bank_mask:0xf
	s_nop 1
	v_add_f32_dpp v5, v4, v4 row_half_mirror row_mask:0xf bank_mask:0xf
	s_nop 1
	v_add_f32_dpp v4, v5, v5 row_mirror row_mask:0xf bank_mask:0xf
	s_nop 1
	v_readlane_b32 s98, v4, 0
	v_readlane_b32 s99, v4, 16
	s_nop 3
	v_mov_b32_e32 v5, s98
	v_add_f32_e32 v5, s99, v5
	v_readlane_b32 s98, v4, 32
	v_readlane_b32 s99, v4, 48
	s_nop 3
	v_add_f32_e32 v5, s98, v5
	v_add_f32_e32 v5, s99, v5
	v_mul_f32_e32 v5, 0x3a800000, v5
	v_add_f32_e32 v5, 0x358637bd, v5
	v_rsq_f32_e32 v6, v5
	s_nop 0
	s_add_u32 s98, s97, 5
	v_pk_mul_f32 v[96:97], v[96:97], v[6:7] op_sel_hi:[1,0]
	v_pk_mul_f32 v[98:99], v[98:99], v[6:7] op_sel_hi:[1,0]
	v_pk_mul_f32 v[100:101], v[100:101], v[6:7] op_sel_hi:[1,0]
	v_pk_mul_f32 v[102:103], v[102:103], v[6:7] op_sel_hi:[1,0]
	v_pk_mul_f32 v[104:105], v[104:105], v[6:7] op_sel_hi:[1,0]
	v_pk_mul_f32 v[106:107], v[106:107], v[6:7] op_sel_hi:[1,0]
	v_pk_mul_f32 v[108:109], v[108:109], v[6:7] op_sel_hi:[1,0]
	v_pk_mul_f32 v[110:111], v[110:111], v[6:7] op_sel_hi:[1,0]
	v_pk_mul_f32 v[96:97], v[96:97], v[112:113]
	v_pk_mul_f32 v[98:99], v[98:99], v[114:115]
	v_pk_mul_f32 v[100:101], v[100:101], v[116:117]
	v_pk_mul_f32 v[102:103], v[102:103], v[118:119]
	v_pk_mul_f32 v[104:105], v[104:105], v[120:121]
	v_pk_mul_f32 v[106:107], v[106:107], v[122:123]
	v_pk_mul_f32 v[108:109], v[108:109], v[124:125]
	v_pk_mul_f32 v[110:111], v[110:111], v[126:127]
	s_lshl_b32 s99, s98, 12
	v_add_u32_e32 v8, s99, v1
	global_store_dwordx4 v8, v[96:99], s[88:89]
	global_store_dwordx4 v8, v[100:103], s[88:89] offset:1024
	global_store_dwordx4 v8, v[104:107], s[88:89] offset:2048
	global_store_dwordx4 v8, v[108:111], s[88:89] offset:3072
	s_add_u32 s98, s97, 11
	s_lshl_b32 s98, s98, 12
	v_add_u32_e32 v3, s98, v1
	global_load_dwordx4 v[96:99], v3, s[88:89] nt
	global_load_dwordx4 v[100:103], v3, s[88:89] offset:1024 nt
	global_load_dwordx4 v[104:107], v3, s[88:89] offset:2048 nt
	global_load_dwordx4 v[108:111], v3, s[88:89] offset:3072 nt
	s_waitcnt vmcnt(40)
	v_mul_f32_e32 v4, v16, v16
	v_fma_f32 v4, v17, v17, v4
	v_fma_f32 v4, v18, v18, v4
	v_fma_f32 v4, v19, v19, v4
	v_fma_f32 v4, v20, v20, v4
	v_fma_f32 v4, v21, v21, v4
	v_fma_f32 v4, v22, v22, v4
	v_fma_f32 v4, v23, v23, v4
	v_fma_f32 v4, v24, v24, v4
	v_fma_f32 v4, v25, v25, v4
	v_fma_f32 v4, v26, v26, v4
	v_fma_f32 v4, v27, v27, v4
	v_fma_f32 v4, v28, v28, v4
	v_fma_f32 v4, v29, v29, v4
	v_fma_f32 v4, v30, v30, v4
	v_fma_f32 v4, v31, v31, v4
	s_nop 1
	v_add_f32_dpp v5, v4, v4 quad_perm:[1,0,3,2] row_mask:0xf bank_mask:0xf
	s_nop 1
	v_add_f32_dpp v4, v5, v5 quad_perm:[2,3,0,1] row_mask:0xf bank_mask:0xf
	s_nop 1
	v_add_f32_dpp v5, v4, v4 row_half_mirror row_mask:0xf bank_mask:0xf
	s_nop 1
	v_add_f32_dpp v4, v5, v5 row_mirror row_mask:0xf bank_mask:0xf
	s_nop 1
	v_readlane_b32 s98, v4, 0
	v_readlane_b32 s99, v4, 16
	s_nop 3
	v_mov_b32_e32 v5, s98
	v_add_f32_e32 v5, s99, v5
	v_readlane_b32 s98, v4, 32
	v_readlane_b32 s99, v4, 48
	s_nop 3
	v_add_f32_e32 v5, s98, v5
	v_add_f32_e32 v5, s99, v5
	v_mul_f32_e32 v5, 0x3a800000, v5
	v_add_f32_e32 v5, 0x358637bd, v5
	v_rsq_f32_e32 v6, v5
	s_nop 0
	s_add_u32 s98, s97, 6
	v_pk_mul_f32 v[16:17], v[16:17], v[6:7] op_sel_hi:[1,0]
	v_pk_mul_f32 v[18:19], v[18:19], v[6:7] op_sel_hi:[1,0]
	v_pk_mul_f32 v[20:21], v[20:21], v[6:7] op_sel_hi:[1,0]
	v_pk_mul_f32 v[22:23], v[22:23], v[6:7] op_sel_hi:[1,0]
	v_pk_mul_f32 v[24:25], v[24:25], v[6:7] op_sel_hi:[1,0]
	v_pk_mul_f32 v[26:27], v[26:27], v[6:7] op_sel_hi:[1,0]
	v_pk_mul_f32 v[28:29], v[28:29], v[6:7] op_sel_hi:[1,0]
	v_pk_mul_f32 v[30:31], v[30:31], v[6:7] op_sel_hi:[1,0]
	v_pk_mul_f32 v[16:17], v[16:17], v[112:113]
	v_pk_mul_f32 v[18:19], v[18:19], v[114:115]
	v_pk_mul_f32 v[20:21], v[20:21], v[116:117]
	v_pk_mul_f32 v[22:23], v[22:23], v[118:119]
	v_pk_mul_f32 v[24:25], v[24:25], v[120:121]
	v_pk_mul_f32 v[26:27], v[26:27], v[122:123]
	v_pk_mul_f32 v[28:29], v[28:29], v[124:125]
	v_pk_mul_f32 v[30:31], v[30:31], v[126:127]
	s_lshl_b32 s99, s98, 12
	v_add_u32_e32 v8, s99, v1
	global_store_dwordx4 v8, v[16:19], s[88:89]
	global_store_dwordx4 v8, v[20:23], s[88:89] offset:1024
	global_store_dwordx4 v8, v[24:27], s[88:89] offset:2048
	global_store_dwordx4 v8, v[28:31], s[88:89] offset:3072
	s_add_u32 s98, s97, 12
	s_lshl_b32 s98, s98, 12
	v_add_u32_e32 v3, s98, v1
	global_load_dwordx4 v[16:19], v3, s[88:89] nt
	global_load_dwordx4 v[20:23], v3, s[88:89] offset:1024 nt
	global_load_dwordx4 v[24:27], v3, s[88:89] offset:2048 nt
	global_load_dwordx4 v[28:31], v3, s[88:89] offset:3072 nt
	s_waitcnt vmcnt(40)
	v_mul_f32_e32 v4, v32, v32
	v_fma_f32 v4, v33, v33, v4
	v_fma_f32 v4, v34, v34, v4
	v_fma_f32 v4, v35, v35, v4
	v_fma_f32 v4, v36, v36, v4
	v_fma_f32 v4, v37, v37, v4
	v_fma_f32 v4, v38, v38, v4
	v_fma_f32 v4, v39, v39, v4
	v_fma_f32 v4, v40, v40, v4
	v_fma_f32 v4, v41, v41, v4
	v_fma_f32 v4, v42, v42, v4
	v_fma_f32 v4, v43, v43, v4
	v_fma_f32 v4, v44, v44, v4
	v_fma_f32 v4, v45, v45, v4
	v_fma_f32 v4, v46, v46, v4
	v_fma_f32 v4, v47, v47, v4
	s_nop 1
	v_add_f32_dpp v5, v4, v4 quad_perm:[1,0,3,2] row_mask:0xf bank_mask:0xf
	s_nop 1
	v_add_f32_dpp v4, v5, v5 quad_perm:[2,3,0,1] row_mask:0xf bank_mask:0xf
	s_nop 1
	v_add_f32_dpp v5, v4, v4 row_half_mirror row_mask:0xf bank_mask:0xf
	s_nop 1
	v_add_f32_dpp v4, v5, v5 row_mirror row_mask:0xf bank_mask:0xf
	s_nop 1
	v_readlane_b32 s98, v4, 0
	v_readlane_b32 s99, v4, 16
	s_nop 3
	v_mov_b32_e32 v5, s98
	v_add_f32_e32 v5, s99, v5
	v_readlane_b32 s98, v4, 32
	v_readlane_b32 s99, v4, 48
	s_nop 3
	v_add_f32_e32 v5, s98, v5
	v_add_f32_e32 v5, s99, v5
	v_mul_f32_e32 v5, 0x3a800000, v5
	v_add_f32_e32 v5, 0x358637bd, v5
	v_rsq_f32_e32 v6, v5
	s_nop 0
	s_add_u32 s98, s97, 7
	v_pk_mul_f32 v[32:33], v[32:33], v[6:7] op_sel_hi:[1,0]
	v_pk_mul_f32 v[34:35], v[34:35], v[6:7] op_sel_hi:[1,0]
	v_pk_mul_f32 v[36:37], v[36:37], v[6:7] op_sel_hi:[1,0]
	v_pk_mul_f32 v[38:39], v[38:39], v[6:7] op_sel_hi:[1,0]
	v_pk_mul_f32 v[40:41], v[40:41], v[6:7] op_sel_hi:[1,0]
	v_pk_mul_f32 v[42:43], v[42:43], v[6:7] op_sel_hi:[1,0]
	v_pk_mul_f32 v[44:45], v[44:45], v[6:7] op_sel_hi:[1,0]
	v_pk_mul_f32 v[46:47], v[46:47], v[6:7] op_sel_hi:[1,0]
	v_pk_mul_f32 v[32:33], v[32:33], v[112:113]
	v_pk_mul_f32 v[34:35], v[34:35], v[114:115]
	v_pk_mul_f32 v[36:37], v[36:37], v[116:117]
	v_pk_mul_f32 v[38:39], v[38:39], v[118:119]
	v_pk_mul_f32 v[40:41], v[40:41], v[120:121]
	v_pk_mul_f32 v[42:43], v[42:43], v[122:123]
	v_pk_mul_f32 v[44:45], v[44:45], v[124:125]
	v_pk_mul_f32 v[46:47], v[46:47], v[126:127]
	s_lshl_b32 s99, s98, 12
	v_add_u32_e32 v8, s99, v1
	global_store_dwordx4 v8, v[32:35], s[88:89]
	global_store_dwordx4 v8, v[36:39], s[88:89] offset:1024
	global_store_dwordx4 v8, v[40:43], s[88:89] offset:2048
	global_store_dwordx4 v8, v[44:47], s[88:89] offset:3072
	s_add_u32 s98, s97, 13
	s_lshl_b32 s98, s98, 12
	v_add_u32_e32 v3, s98, v1
	global_load_dwordx4 v[32:35], v3, s[88:89] nt
	global_load_dwordx4 v[36:39], v3, s[88:89] offset:1024 nt
	global_load_dwordx4 v[40:43], v3, s[88:89] offset:2048 nt
	global_load_dwordx4 v[44:47], v3, s[88:89] offset:3072 nt
	s_waitcnt vmcnt(40)
	v_mul_f32_e32 v4, v48, v48
	v_fma_f32 v4, v49, v49, v4
	v_fma_f32 v4, v50, v50, v4
	v_fma_f32 v4, v51, v51, v4
	v_fma_f32 v4, v52, v52, v4
	v_fma_f32 v4, v53, v53, v4
	v_fma_f32 v4, v54, v54, v4
	v_fma_f32 v4, v55, v55, v4
	v_fma_f32 v4, v56, v56, v4
	v_fma_f32 v4, v57, v57, v4
	v_fma_f32 v4, v58, v58, v4
	v_fma_f32 v4, v59, v59, v4
	v_fma_f32 v4, v60, v60, v4
	v_fma_f32 v4, v61, v61, v4
	v_fma_f32 v4, v62, v62, v4
	v_fma_f32 v4, v63, v63, v4
	s_nop 1
	v_add_f32_dpp v5, v4, v4 quad_perm:[1,0,3,2] row_mask:0xf bank_mask:0xf
	s_nop 1
	v_add_f32_dpp v4, v5, v5 quad_perm:[2,3,0,1] row_mask:0xf bank_mask:0xf
	s_nop 1
	v_add_f32_dpp v5, v4, v4 row_half_mirror row_mask:0xf bank_mask:0xf
	s_nop 1
	v_add_f32_dpp v4, v5, v5 row_mirror row_mask:0xf bank_mask:0xf
	s_nop 1
	v_readlane_b32 s98, v4, 0
	v_readlane_b32 s99, v4, 16
	s_nop 3
	v_mov_b32_e32 v5, s98
	v_add_f32_e32 v5, s99, v5
	v_readlane_b32 s98, v4, 32
	v_readlane_b32 s99, v4, 48
	s_nop 3
	v_add_f32_e32 v5, s98, v5
	v_add_f32_e32 v5, s99, v5
	v_mul_f32_e32 v5, 0x3a800000, v5
	v_add_f32_e32 v5, 0x358637bd, v5
	v_rsq_f32_e32 v6, v5
	s_nop 0
	s_add_u32 s98, s97, 8
	v_pk_mul_f32 v[48:49], v[48:49], v[6:7] op_sel_hi:[1,0]
	v_pk_mul_f32 v[50:51], v[50:51], v[6:7] op_sel_hi:[1,0]
	v_pk_mul_f32 v[52:53], v[52:53], v[6:7] op_sel_hi:[1,0]
	v_pk_mul_f32 v[54:55], v[54:55], v[6:7] op_sel_hi:[1,0]
	v_pk_mul_f32 v[56:57], v[56:57], v[6:7] op_sel_hi:[1,0]
	v_pk_mul_f32 v[58:59], v[58:59], v[6:7] op_sel_hi:[1,0]
	v_pk_mul_f32 v[60:61], v[60:61], v[6:7] op_sel_hi:[1,0]
	v_pk_mul_f32 v[62:63], v[62:63], v[6:7] op_sel_hi:[1,0]
	v_pk_mul_f32 v[48:49], v[48:49], v[112:113]
	v_pk_mul_f32 v[50:51], v[50:51], v[114:115]
	v_pk_mul_f32 v[52:53], v[52:53], v[116:117]
	v_pk_mul_f32 v[54:55], v[54:55], v[118:119]
	v_pk_mul_f32 v[56:57], v[56:57], v[120:121]
	v_pk_mul_f32 v[58:59], v[58:59], v[122:123]
	v_pk_mul_f32 v[60:61], v[60:61], v[124:125]
	v_pk_mul_f32 v[62:63], v[62:63], v[126:127]
	s_lshl_b32 s99, s98, 12
	v_add_u32_e32 v8, s99, v1
	global_store_dwordx4 v8, v[48:51], s[88:89]
	global_store_dwordx4 v8, v[52:55], s[88:89] offset:1024
	global_store_dwordx4 v8, v[56:59], s[88:89] offset:2048
	global_store_dwordx4 v8, v[60:63], s[88:89] offset:3072
	s_add_u32 s98, s97, 14
	s_lshl_b32 s98, s98, 12
	v_add_u32_e32 v3, s98, v1
	global_load_dwordx4 v[48:51], v3, s[88:89] nt
	global_load_dwordx4 v[52:55], v3, s[88:89] offset:1024 nt
	global_load_dwordx4 v[56:59], v3, s[88:89] offset:2048 nt
	global_load_dwordx4 v[60:63], v3, s[88:89] offset:3072 nt
	s_waitcnt vmcnt(40)
	v_mul_f32_e32 v4, v64, v64
	v_fma_f32 v4, v65, v65, v4
	v_fma_f32 v4, v66, v66, v4
	v_fma_f32 v4, v67, v67, v4
	v_fma_f32 v4, v68, v68, v4
	v_fma_f32 v4, v69, v69, v4
	v_fma_f32 v4, v70, v70, v4
	v_fma_f32 v4, v71, v71, v4
	v_fma_f32 v4, v72, v72, v4
	v_fma_f32 v4, v73, v73, v4
	v_fma_f32 v4, v74, v74, v4
	v_fma_f32 v4, v75, v75, v4
	v_fma_f32 v4, v76, v76, v4
	v_fma_f32 v4, v77, v77, v4
	v_fma_f32 v4, v78, v78, v4
	v_fma_f32 v4, v79, v79, v4
	s_nop 1
	v_add_f32_dpp v5, v4, v4 quad_perm:[1,0,3,2] row_mask:0xf bank_mask:0xf
	s_nop 1
	v_add_f32_dpp v4, v5, v5 quad_perm:[2,3,0,1] row_mask:0xf bank_mask:0xf
	s_nop 1
	v_add_f32_dpp v5, v4, v4 row_half_mirror row_mask:0xf bank_mask:0xf
	s_nop 1
	v_add_f32_dpp v4, v5, v5 row_mirror row_mask:0xf bank_mask:0xf
	s_nop 1
	v_readlane_b32 s98, v4, 0
	v_readlane_b32 s99, v4, 16
	s_nop 3
	v_mov_b32_e32 v5, s98
	v_add_f32_e32 v5, s99, v5
	v_readlane_b32 s98, v4, 32
	v_readlane_b32 s99, v4, 48
	s_nop 3
	v_add_f32_e32 v5, s98, v5
	v_add_f32_e32 v5, s99, v5
	v_mul_f32_e32 v5, 0x3a800000, v5
	v_add_f32_e32 v5, 0x358637bd, v5
	v_rsq_f32_e32 v6, v5
	s_nop 0
	s_add_u32 s98, s97, 9
	v_pk_mul_f32 v[64:65], v[64:65], v[6:7] op_sel_hi:[1,0]
	v_pk_mul_f32 v[66:67], v[66:67], v[6:7] op_sel_hi:[1,0]
	v_pk_mul_f32 v[68:69], v[68:69], v[6:7] op_sel_hi:[1,0]
	v_pk_mul_f32 v[70:71], v[70:71], v[6:7] op_sel_hi:[1,0]
	v_pk_mul_f32 v[72:73], v[72:73], v[6:7] op_sel_hi:[1,0]
	v_pk_mul_f32 v[74:75], v[74:75], v[6:7] op_sel_hi:[1,0]
	v_pk_mul_f32 v[76:77], v[76:77], v[6:7] op_sel_hi:[1,0]
	v_pk_mul_f32 v[78:79], v[78:79], v[6:7] op_sel_hi:[1,0]
	v_pk_mul_f32 v[64:65], v[64:65], v[112:113]
	v_pk_mul_f32 v[66:67], v[66:67], v[114:115]
	v_pk_mul_f32 v[68:69], v[68:69], v[116:117]
	v_pk_mul_f32 v[70:71], v[70:71], v[118:119]
	v_pk_mul_f32 v[72:73], v[72:73], v[120:121]
	v_pk_mul_f32 v[74:75], v[74:75], v[122:123]
	v_pk_mul_f32 v[76:77], v[76:77], v[124:125]
	v_pk_mul_f32 v[78:79], v[78:79], v[126:127]
	s_lshl_b32 s99, s98, 12
	v_add_u32_e32 v8, s99, v1
	global_store_dwordx4 v8, v[64:67], s[88:89]
	global_store_dwordx4 v8, v[68:71], s[88:89] offset:1024
	global_store_dwordx4 v8, v[72:75], s[88:89] offset:2048
	global_store_dwordx4 v8, v[76:79], s[88:89] offset:3072
	s_add_u32 s98, s97, 15
	s_lshl_b32 s98, s98, 12
	v_add_u32_e32 v3, s98, v1
	global_load_dwordx4 v[64:67], v3, s[88:89] nt
	global_load_dwordx4 v[68:71], v3, s[88:89] offset:1024 nt
	global_load_dwordx4 v[72:75], v3, s[88:89] offset:2048 nt
	global_load_dwordx4 v[76:79], v3, s[88:89] offset:3072 nt
	s_waitcnt vmcnt(40)
	v_mul_f32_e32 v4, v80, v80
	v_fma_f32 v4, v81, v81, v4
	v_fma_f32 v4, v82, v82, v4
	v_fma_f32 v4, v83, v83, v4
	v_fma_f32 v4, v84, v84, v4
	v_fma_f32 v4, v85, v85, v4
	v_fma_f32 v4, v86, v86, v4
	v_fma_f32 v4, v87, v87, v4
	v_fma_f32 v4, v88, v88, v4
	v_fma_f32 v4, v89, v89, v4
	v_fma_f32 v4, v90, v90, v4
	v_fma_f32 v4, v91, v91, v4
	v_fma_f32 v4, v92, v92, v4
	v_fma_f32 v4, v93, v93, v4
	v_fma_f32 v4, v94, v94, v4
	v_fma_f32 v4, v95, v95, v4
	s_nop 1
	v_add_f32_dpp v5, v4, v4 quad_perm:[1,0,3,2] row_mask:0xf bank_mask:0xf
	s_nop 1
	v_add_f32_dpp v4, v5, v5 quad_perm:[2,3,0,1] row_mask:0xf bank_mask:0xf
	s_nop 1
	v_add_f32_dpp v5, v4, v4 row_half_mirror row_mask:0xf bank_mask:0xf
	s_nop 1
	v_add_f32_dpp v4, v5, v5 row_mirror row_mask:0xf bank_mask:0xf
	s_nop 1
	v_readlane_b32 s98, v4, 0
	v_readlane_b32 s99, v4, 16
	s_nop 3
	v_mov_b32_e32 v5, s98
	v_add_f32_e32 v5, s99, v5
	v_readlane_b32 s98, v4, 32
	v_readlane_b32 s99, v4, 48
	s_nop 3
	v_add_f32_e32 v5, s98, v5
	v_add_f32_e32 v5, s99, v5
	v_mul_f32_e32 v5, 0x3a800000, v5
	v_add_f32_e32 v5, 0x358637bd, v5
	v_rsq_f32_e32 v6, v5
	s_nop 0
	s_add_u32 s98, s97, 10
	v_pk_mul_f32 v[80:81], v[80:81], v[6:7] op_sel_hi:[1,0]
	v_pk_mul_f32 v[82:83], v[82:83], v[6:7] op_sel_hi:[1,0]
	v_pk_mul_f32 v[84:85], v[84:85], v[6:7] op_sel_hi:[1,0]
	v_pk_mul_f32 v[86:87], v[86:87], v[6:7] op_sel_hi:[1,0]
	v_pk_mul_f32 v[88:89], v[88:89], v[6:7] op_sel_hi:[1,0]
	v_pk_mul_f32 v[90:91], v[90:91], v[6:7] op_sel_hi:[1,0]
	v_pk_mul_f32 v[92:93], v[92:93], v[6:7] op_sel_hi:[1,0]
	v_pk_mul_f32 v[94:95], v[94:95], v[6:7] op_sel_hi:[1,0]
	v_pk_mul_f32 v[80:81], v[80:81], v[112:113]
	v_pk_mul_f32 v[82:83], v[82:83], v[114:115]
	v_pk_mul_f32 v[84:85], v[84:85], v[116:117]
	v_pk_mul_f32 v[86:87], v[86:87], v[118:119]
	v_pk_mul_f32 v[88:89], v[88:89], v[120:121]
	v_pk_mul_f32 v[90:91], v[90:91], v[122:123]
	v_pk_mul_f32 v[92:93], v[92:93], v[124:125]
	v_pk_mul_f32 v[94:95], v[94:95], v[126:127]
	s_lshl_b32 s99, s98, 12
	v_add_u32_e32 v8, s99, v1
	global_store_dwordx4 v8, v[80:83], s[88:89]
	global_store_dwordx4 v8, v[84:87], s[88:89] offset:1024
	global_store_dwordx4 v8, v[88:91], s[88:89] offset:2048
	global_store_dwordx4 v8, v[92:95], s[88:89] offset:3072
	s_waitcnt vmcnt(36)
	v_mul_f32_e32 v4, v96, v96
	v_fma_f32 v4, v97, v97, v4
	v_fma_f32 v4, v98, v98, v4
	v_fma_f32 v4, v99, v99, v4
	v_fma_f32 v4, v100, v100, v4
	v_fma_f32 v4, v101, v101, v4
	v_fma_f32 v4, v102, v102, v4
	v_fma_f32 v4, v103, v103, v4
	v_fma_f32 v4, v104, v104, v4
	v_fma_f32 v4, v105, v105, v4
	v_fma_f32 v4, v106, v106, v4
	v_fma_f32 v4, v107, v107, v4
	v_fma_f32 v4, v108, v108, v4
	v_fma_f32 v4, v109, v109, v4
	v_fma_f32 v4, v110, v110, v4
	v_fma_f32 v4, v111, v111, v4
	s_nop 1
	v_add_f32_dpp v5, v4, v4 quad_perm:[1,0,3,2] row_mask:0xf bank_mask:0xf
	s_nop 1
	v_add_f32_dpp v4, v5, v5 quad_perm:[2,3,0,1] row_mask:0xf bank_mask:0xf
	s_nop 1
	v_add_f32_dpp v5, v4, v4 row_half_mirror row_mask:0xf bank_mask:0xf
	s_nop 1
	v_add_f32_dpp v4, v5, v5 row_mirror row_mask:0xf bank_mask:0xf
	s_nop 1
	v_readlane_b32 s98, v4, 0
	v_readlane_b32 s99, v4, 16
	s_nop 3
	v_mov_b32_e32 v5, s98
	v_add_f32_e32 v5, s99, v5
	v_readlane_b32 s98, v4, 32
	v_readlane_b32 s99, v4, 48
	s_nop 3
	v_add_f32_e32 v5, s98, v5
	v_add_f32_e32 v5, s99, v5
	v_mul_f32_e32 v5, 0x3a800000, v5
	v_add_f32_e32 v5, 0x358637bd, v5
	v_rsq_f32_e32 v6, v5
	s_nop 0
	s_add_u32 s98, s97, 11
	v_pk_mul_f32 v[96:97], v[96:97], v[6:7] op_sel_hi:[1,0]
	v_pk_mul_f32 v[98:99], v[98:99], v[6:7] op_sel_hi:[1,0]
	v_pk_mul_f32 v[100:101], v[100:101], v[6:7] op_sel_hi:[1,0]
	v_pk_mul_f32 v[102:103], v[102:103], v[6:7] op_sel_hi:[1,0]
	v_pk_mul_f32 v[104:105], v[104:105], v[6:7] op_sel_hi:[1,0]
	v_pk_mul_f32 v[106:107], v[106:107], v[6:7] op_sel_hi:[1,0]
	v_pk_mul_f32 v[108:109], v[108:109], v[6:7] op_sel_hi:[1,0]
	v_pk_mul_f32 v[110:111], v[110:111], v[6:7] op_sel_hi:[1,0]
	v_pk_mul_f32 v[96:97], v[96:97], v[112:113]
	v_pk_mul_f32 v[98:99], v[98:99], v[114:115]
	v_pk_mul_f32 v[100:101], v[100:101], v[116:117]
	v_pk_mul_f32 v[102:103], v[102:103], v[118:119]
	v_pk_mul_f32 v[104:105], v[104:105], v[120:121]
	v_pk_mul_f32 v[106:107], v[106:107], v[122:123]
	v_pk_mul_f32 v[108:109], v[108:109], v[124:125]
	v_pk_mul_f32 v[110:111], v[110:111], v[126:127]
	s_lshl_b32 s99, s98, 12
	v_add_u32_e32 v8, s99, v1
	global_store_dwordx4 v8, v[96:99], s[88:89]
	global_store_dwordx4 v8, v[100:103], s[88:89] offset:1024
	global_store_dwordx4 v8, v[104:107], s[88:89] offset:2048
	global_store_dwordx4 v8, v[108:111], s[88:89] offset:3072
	s_waitcnt vmcnt(32)
	v_mul_f32_e32 v4, v16, v16
	v_fma_f32 v4, v17, v17, v4
	v_fma_f32 v4, v18, v18, v4
	v_fma_f32 v4, v19, v19, v4
	v_fma_f32 v4, v20, v20, v4
	v_fma_f32 v4, v21, v21, v4
	v_fma_f32 v4, v22, v22, v4
	v_fma_f32 v4, v23, v23, v4
	v_fma_f32 v4, v24, v24, v4
	v_fma_f32 v4, v25, v25, v4
	v_fma_f32 v4, v26, v26, v4
	v_fma_f32 v4, v27, v27, v4
	v_fma_f32 v4, v28, v28, v4
	v_fma_f32 v4, v29, v29, v4
	v_fma_f32 v4, v30, v30, v4
	v_fma_f32 v4, v31, v31, v4
	s_nop 1
	v_add_f32_dpp v5, v4, v4 quad_perm:[1,0,3,2] row_mask:0xf bank_mask:0xf
	s_nop 1
	v_add_f32_dpp v4, v5, v5 quad_perm:[2,3,0,1] row_mask:0xf bank_mask:0xf
	s_nop 1
	v_add_f32_dpp v5, v4, v4 row_half_mirror row_mask:0xf bank_mask:0xf
	s_nop 1
	v_add_f32_dpp v4, v5, v5 row_mirror row_mask:0xf bank_mask:0xf
	s_nop 1
	v_readlane_b32 s98, v4, 0
	v_readlane_b32 s99, v4, 16
	s_nop 3
	v_mov_b32_e32 v5, s98
	v_add_f32_e32 v5, s99, v5
	v_readlane_b32 s98, v4, 32
	v_readlane_b32 s99, v4, 48
	s_nop 3
	v_add_f32_e32 v5, s98, v5
	v_add_f32_e32 v5, s99, v5
	v_mul_f32_e32 v5, 0x3a800000, v5
	v_add_f32_e32 v5, 0x358637bd, v5
	v_rsq_f32_e32 v6, v5
	s_nop 0
	s_add_u32 s98, s97, 12
	v_pk_mul_f32 v[16:17], v[16:17], v[6:7] op_sel_hi:[1,0]
	v_pk_mul_f32 v[18:19], v[18:19], v[6:7] op_sel_hi:[1,0]
	v_pk_mul_f32 v[20:21], v[20:21], v[6:7] op_sel_hi:[1,0]
	v_pk_mul_f32 v[22:23], v[22:23], v[6:7] op_sel_hi:[1,0]
	v_pk_mul_f32 v[24:25], v[24:25], v[6:7] op_sel_hi:[1,0]
	v_pk_mul_f32 v[26:27], v[26:27], v[6:7] op_sel_hi:[1,0]
	v_pk_mul_f32 v[28:29], v[28:29], v[6:7] op_sel_hi:[1,0]
	v_pk_mul_f32 v[30:31], v[30:31], v[6:7] op_sel_hi:[1,0]
	v_pk_mul_f32 v[16:17], v[16:17], v[112:113]
	v_pk_mul_f32 v[18:19], v[18:19], v[114:115]
	v_pk_mul_f32 v[20:21], v[20:21], v[116:117]
	v_pk_mul_f32 v[22:23], v[22:23], v[118:119]
	v_pk_mul_f32 v[24:25], v[24:25], v[120:121]
	v_pk_mul_f32 v[26:27], v[26:27], v[122:123]
	v_pk_mul_f32 v[28:29], v[28:29], v[124:125]
	v_pk_mul_f32 v[30:31], v[30:31], v[126:127]
	s_lshl_b32 s99, s98, 12
	v_add_u32_e32 v8, s99, v1
	global_store_dwordx4 v8, v[16:19], s[88:89]
	global_store_dwordx4 v8, v[20:23], s[88:89] offset:1024
	global_store_dwordx4 v8, v[24:27], s[88:89] offset:2048
	global_store_dwordx4 v8, v[28:31], s[88:89] offset:3072
	s_waitcnt vmcnt(28)
	v_mul_f32_e32 v4, v32, v32
	v_fma_f32 v4, v33, v33, v4
	v_fma_f32 v4, v34, v34, v4
	v_fma_f32 v4, v35, v35, v4
	v_fma_f32 v4, v36, v36, v4
	v_fma_f32 v4, v37, v37, v4
	v_fma_f32 v4, v38, v38, v4
	v_fma_f32 v4, v39, v39, v4
	v_fma_f32 v4, v40, v40, v4
	v_fma_f32 v4, v41, v41, v4
	v_fma_f32 v4, v42, v42, v4
	v_fma_f32 v4, v43, v43, v4
	v_fma_f32 v4, v44, v44, v4
	v_fma_f32 v4, v45, v45, v4
	v_fma_f32 v4, v46, v46, v4
	v_fma_f32 v4, v47, v47, v4
	s_nop 1
	v_add_f32_dpp v5, v4, v4 quad_perm:[1,0,3,2] row_mask:0xf bank_mask:0xf
	s_nop 1
	v_add_f32_dpp v4, v5, v5 quad_perm:[2,3,0,1] row_mask:0xf bank_mask:0xf
	s_nop 1
	v_add_f32_dpp v5, v4, v4 row_half_mirror row_mask:0xf bank_mask:0xf
	s_nop 1
	v_add_f32_dpp v4, v5, v5 row_mirror row_mask:0xf bank_mask:0xf
	s_nop 1
	v_readlane_b32 s98, v4, 0
	v_readlane_b32 s99, v4, 16
	s_nop 3
	v_mov_b32_e32 v5, s98
	v_add_f32_e32 v5, s99, v5
	v_readlane_b32 s98, v4, 32
	v_readlane_b32 s99, v4, 48
	s_nop 3
	v_add_f32_e32 v5, s98, v5
	v_add_f32_e32 v5, s99, v5
	v_mul_f32_e32 v5, 0x3a800000, v5
	v_add_f32_e32 v5, 0x358637bd, v5
	v_rsq_f32_e32 v6, v5
	s_nop 0
	s_add_u32 s98, s97, 13
	v_pk_mul_f32 v[32:33], v[32:33], v[6:7] op_sel_hi:[1,0]
	v_pk_mul_f32 v[34:35], v[34:35], v[6:7] op_sel_hi:[1,0]
	v_pk_mul_f32 v[36:37], v[36:37], v[6:7] op_sel_hi:[1,0]
	v_pk_mul_f32 v[38:39], v[38:39], v[6:7] op_sel_hi:[1,0]
	v_pk_mul_f32 v[40:41], v[40:41], v[6:7] op_sel_hi:[1,0]
	v_pk_mul_f32 v[42:43], v[42:43], v[6:7] op_sel_hi:[1,0]
	v_pk_mul_f32 v[44:45], v[44:45], v[6:7] op_sel_hi:[1,0]
	v_pk_mul_f32 v[46:47], v[46:47], v[6:7] op_sel_hi:[1,0]
	v_pk_mul_f32 v[32:33], v[32:33], v[112:113]
	v_pk_mul_f32 v[34:35], v[34:35], v[114:115]
	v_pk_mul_f32 v[36:37], v[36:37], v[116:117]
	v_pk_mul_f32 v[38:39], v[38:39], v[118:119]
	v_pk_mul_f32 v[40:41], v[40:41], v[120:121]
	v_pk_mul_f32 v[42:43], v[42:43], v[122:123]
	v_pk_mul_f32 v[44:45], v[44:45], v[124:125]
	v_pk_mul_f32 v[46:47], v[46:47], v[126:127]
	s_lshl_b32 s99, s98, 12
	v_add_u32_e32 v8, s99, v1
	global_store_dwordx4 v8, v[32:35], s[88:89]
	global_store_dwordx4 v8, v[36:39], s[88:89] offset:1024
	global_store_dwordx4 v8, v[40:43], s[88:89] offset:2048
	global_store_dwordx4 v8, v[44:47], s[88:89] offset:3072
	s_waitcnt vmcnt(24)
	v_mul_f32_e32 v4, v48, v48
	v_fma_f32 v4, v49, v49, v4
	v_fma_f32 v4, v50, v50, v4
	v_fma_f32 v4, v51, v51, v4
	v_fma_f32 v4, v52, v52, v4
	v_fma_f32 v4, v53, v53, v4
	v_fma_f32 v4, v54, v54, v4
	v_fma_f32 v4, v55, v55, v4
	v_fma_f32 v4, v56, v56, v4
	v_fma_f32 v4, v57, v57, v4
	v_fma_f32 v4, v58, v58, v4
	v_fma_f32 v4, v59, v59, v4
	v_fma_f32 v4, v60, v60, v4
	v_fma_f32 v4, v61, v61, v4
	v_fma_f32 v4, v62, v62, v4
	v_fma_f32 v4, v63, v63, v4
	s_nop 1
	v_add_f32_dpp v5, v4, v4 quad_perm:[1,0,3,2] row_mask:0xf bank_mask:0xf
	s_nop 1
	v_add_f32_dpp v4, v5, v5 quad_perm:[2,3,0,1] row_mask:0xf bank_mask:0xf
	s_nop 1
	v_add_f32_dpp v5, v4, v4 row_half_mirror row_mask:0xf bank_mask:0xf
	s_nop 1
	v_add_f32_dpp v4, v5, v5 row_mirror row_mask:0xf bank_mask:0xf
	s_nop 1
	v_readlane_b32 s98, v4, 0
	v_readlane_b32 s99, v4, 16
	s_nop 3
	v_mov_b32_e32 v5, s98
	v_add_f32_e32 v5, s99, v5
	v_readlane_b32 s98, v4, 32
	v_readlane_b32 s99, v4, 48
	s_nop 3
	v_add_f32_e32 v5, s98, v5
	v_add_f32_e32 v5, s99, v5
	v_mul_f32_e32 v5, 0x3a800000, v5
	v_add_f32_e32 v5, 0x358637bd, v5
	v_rsq_f32_e32 v6, v5
	s_nop 0
	s_add_u32 s98, s97, 14
	v_pk_mul_f32 v[48:49], v[48:49], v[6:7] op_sel_hi:[1,0]
	v_pk_mul_f32 v[50:51], v[50:51], v[6:7] op_sel_hi:[1,0]
	v_pk_mul_f32 v[52:53], v[52:53], v[6:7] op_sel_hi:[1,0]
	v_pk_mul_f32 v[54:55], v[54:55], v[6:7] op_sel_hi:[1,0]
	v_pk_mul_f32 v[56:57], v[56:57], v[6:7] op_sel_hi:[1,0]
	v_pk_mul_f32 v[58:59], v[58:59], v[6:7] op_sel_hi:[1,0]
	v_pk_mul_f32 v[60:61], v[60:61], v[6:7] op_sel_hi:[1,0]
	v_pk_mul_f32 v[62:63], v[62:63], v[6:7] op_sel_hi:[1,0]
	v_pk_mul_f32 v[48:49], v[48:49], v[112:113]
	v_pk_mul_f32 v[50:51], v[50:51], v[114:115]
	v_pk_mul_f32 v[52:53], v[52:53], v[116:117]
	v_pk_mul_f32 v[54:55], v[54:55], v[118:119]
	v_pk_mul_f32 v[56:57], v[56:57], v[120:121]
	v_pk_mul_f32 v[58:59], v[58:59], v[122:123]
	v_pk_mul_f32 v[60:61], v[60:61], v[124:125]
	v_pk_mul_f32 v[62:63], v[62:63], v[126:127]
	s_lshl_b32 s99, s98, 12
	v_add_u32_e32 v8, s99, v1
	global_store_dwordx4 v8, v[48:51], s[88:89]
	global_store_dwordx4 v8, v[52:55], s[88:89] offset:1024
	global_store_dwordx4 v8, v[56:59], s[88:89] offset:2048
	global_store_dwordx4 v8, v[60:63], s[88:89] offset:3072
	s_waitcnt vmcnt(20)
	v_mul_f32_e32 v4, v64, v64
	v_fma_f32 v4, v65, v65, v4
	v_fma_f32 v4, v66, v66, v4
	v_fma_f32 v4, v67, v67, v4
	v_fma_f32 v4, v68, v68, v4
	v_fma_f32 v4, v69, v69, v4
	v_fma_f32 v4, v70, v70, v4
	v_fma_f32 v4, v71, v71, v4
	v_fma_f32 v4, v72, v72, v4
	v_fma_f32 v4, v73, v73, v4
	v_fma_f32 v4, v74, v74, v4
	v_fma_f32 v4, v75, v75, v4
	v_fma_f32 v4, v76, v76, v4
	v_fma_f32 v4, v77, v77, v4
	v_fma_f32 v4, v78, v78, v4
	v_fma_f32 v4, v79, v79, v4
	s_nop 1
	v_add_f32_dpp v5, v4, v4 quad_perm:[1,0,3,2] row_mask:0xf bank_mask:0xf
	s_nop 1
	v_add_f32_dpp v4, v5, v5 quad_perm:[2,3,0,1] row_mask:0xf bank_mask:0xf
	s_nop 1
	v_add_f32_dpp v5, v4, v4 row_half_mirror row_mask:0xf bank_mask:0xf
	s_nop 1
	v_add_f32_dpp v4, v5, v5 row_mirror row_mask:0xf bank_mask:0xf
	s_nop 1
	v_readlane_b32 s98, v4, 0
	v_readlane_b32 s99, v4, 16
	s_nop 3
	v_mov_b32_e32 v5, s98
	v_add_f32_e32 v5, s99, v5
	v_readlane_b32 s98, v4, 32
	v_readlane_b32 s99, v4, 48
	s_nop 3
	v_add_f32_e32 v5, s98, v5
	v_add_f32_e32 v5, s99, v5
	v_mul_f32_e32 v5, 0x3a800000, v5
	v_add_f32_e32 v5, 0x358637bd, v5
	v_rsq_f32_e32 v6, v5
	s_nop 0
	s_add_u32 s98, s97, 15
	v_pk_mul_f32 v[64:65], v[64:65], v[6:7] op_sel_hi:[1,0]
	v_pk_mul_f32 v[66:67], v[66:67], v[6:7] op_sel_hi:[1,0]
	v_pk_mul_f32 v[68:69], v[68:69], v[6:7] op_sel_hi:[1,0]
	v_pk_mul_f32 v[70:71], v[70:71], v[6:7] op_sel_hi:[1,0]
	v_pk_mul_f32 v[72:73], v[72:73], v[6:7] op_sel_hi:[1,0]
	v_pk_mul_f32 v[74:75], v[74:75], v[6:7] op_sel_hi:[1,0]
	v_pk_mul_f32 v[76:77], v[76:77], v[6:7] op_sel_hi:[1,0]
	v_pk_mul_f32 v[78:79], v[78:79], v[6:7] op_sel_hi:[1,0]
	v_pk_mul_f32 v[64:65], v[64:65], v[112:113]
	v_pk_mul_f32 v[66:67], v[66:67], v[114:115]
	v_pk_mul_f32 v[68:69], v[68:69], v[116:117]
	v_pk_mul_f32 v[70:71], v[70:71], v[118:119]
	v_pk_mul_f32 v[72:73], v[72:73], v[120:121]
	v_pk_mul_f32 v[74:75], v[74:75], v[122:123]
	v_pk_mul_f32 v[76:77], v[76:77], v[124:125]
	v_pk_mul_f32 v[78:79], v[78:79], v[126:127]
	s_lshl_b32 s99, s98, 12
	v_add_u32_e32 v8, s99, v1
	global_store_dwordx4 v8, v[64:67], s[88:89]
	global_store_dwordx4 v8, v[68:71], s[88:89] offset:1024
	global_store_dwordx4 v8, v[72:75], s[88:89] offset:2048
	global_store_dwordx4 v8, v[76:79], s[88:89] offset:3072
	s_waitcnt vmcnt(0)
